# ret S2 tail: second GI quad read hoisted into the first P block (last exposed LDS round trip in the scan units)
# baseline (speedup 1.0000x reference)
; __device__ __forceinline__ unsigned cvt_pk_bf16(float lo, float hi) { unsigned r; asm("v_cvt_pk_bf16_f32 %0, %1, %2" : "=v"(r) : "v"(lo), "v"(hi)); return r; }
; template <int DK, int DV, bool SEPQ> ...
;     ...
;         const float gi_i = GI[16 * m + fr];
;         const int n0 = 2 * hw, n1 = 2 * hw + 1; const bool do0 = n0 <= m, do1 = n1 <= m;
;         f32x4 acc0 = {0.f, 0.f, 0.f, 0.f}, acc1 = {0.f, 0.f, 0.f, 0.f};
; #pragma unroll
;         for (int vt = 0; vt < NVTW; ++vt) O[vt] = (f32x4){0.f, 0.f, 0.f, 0.f};
; #pragma unroll
;         for (int ks = 0; ks < DK / 32; ++ks) {
;             const bf16x8 qf = *(const bf16x8*)(QA + (16 * m + fr) * LQ + 32 * ks + 8 * fq);
;             if (do0) { const bf16x8 kf = *(const bf16x8*)(KB + (16 * n0 + fr) * LQ + 32 * ks + 8 * fq); acc0 = __builtin_amdgcn_mfma_f32_16x16x32_bf16(kf, qf, acc0, 0, 0, 0); }
;             if (do1) { const bf16x8 kf = *(const bf16x8*)(KB + (16 * n1 + fr) * LQ + 32 * ks + 8 * fq); acc1 = __builtin_amdgcn_mfma_f32_16x16x32_bf16(kf, qf, acc1, 0, 0, 0); }
;             bf16x8 qs = qf; if (SEPQ) qs = *(const bf16x8*)(QS + (16 * m + fr) * LQ + 32 * ks + 8 * fq);
; #pragma unroll
; __device__ __forceinline__ void ret_block(ArgsP a_, unsigned char* smem) { const ArgsP a = a_;
;     ...
;         { const int cp = tid & 127, jq = tid >> 7;
;           float dj[16];
; #pragma unroll
;           for (int q4 = 0; q4 < 4; ++q4) { const f32x4 t = *(const f32x4*)(DECJ + 16 * jq + 4 * q4); dj[4 * q4] = t[0]; dj[4 * q4 + 1] = t[1]; dj[4 * q4 + 2] = t[2]; dj[4 * q4 + 3] = t[3]; }
;           unsigned lo[8], hi[8];
; #pragma unroll
;           for (int e = 0; e < 8; ++e) { const int j = 16 * jq + 2 * e; const unsigned w0 = *(const unsigned*)(KB + j * LQ + 2 * cp), w1 = *(const unsigned*)(KB + (j + 1) * LQ + 2 * cp);
;               lo[e] = cvt_pk_bf16(__uint_as_float(w0 << 16) * dj[2 * e], __uint_as_float(w1 << 16) * dj[2 * e + 1]);
;               hi[e] = cvt_pk_bf16(__uint_as_float(w0 & 0xffff0000u) * dj[2 * e], __uint_as_float(w1 & 0xffff0000u) * dj[2 * e + 1]); }
;           *(u32x4*)(KT + (2 * cp) * LJ + 16 * jq) = (u32x4){lo[0], lo[1], lo[2], lo[3]}; *(u32x4*)(KT + (2 * cp) * LJ + 16 * jq + 8) = (u32x4){lo[4], lo[5], lo[6], lo[7]};
;           *(u32x4*)(KT + (2 * cp + 1) * LJ + 16 * jq) = (u32x4){hi[0], hi[1], hi[2], hi[3]}; *(u32x4*)(KT + (2 * cp + 1) * LJ + 16 * jq + 8) = (u32x4){hi[4], hi[5], hi[6], hi[7]}; }
.LBB0_269:
	ds_read_b128 v[214:217], v142
	ds_read_b128 v[218:221], v142 offset:16
	ds_read_b128 v[222:225], v142 offset:32
	ds_read_b128 v[226:229], v142 offset:48
	ds_read_b32 v230, v140 offset:33792
	ds_read_b32 v231, v141 offset:34320
	ds_read_b32 v232, v140 offset:34848
	ds_read_b32 v233, v141 offset:35376
	ds_read_b32 v234, v140 offset:35904
	ds_read_b32 v235, v141 offset:36432
	ds_read_b32 v236, v140 offset:36960
	ds_read_b32 v237, v141 offset:37488
	ds_read_b32 v238, v140 offset:38016
	ds_read_b32 v239, v141 offset:38544
	ds_read_b32 v240, v140 offset:39072
	s_waitcnt lgkmcnt(10)
	v_lshlrev_b32_e32 v19, 16, v230
	ds_read_b32 v241, v141 offset:39600
	ds_read_b32 v242, v140 offset:40128
	ds_read_b32 v243, v141 offset:40656
	ds_read_b32 v244, v140 offset:41184
	ds_read_b32 v245, v141 offset:41712
	s_waitcnt lgkmcnt(14)
	v_lshlrev_b32_e32 v80, 16, v231
	v_and_b32_e32 v16, 0xffff0000, v230
	v_and_b32_e32 v18, 0xffff0000, v231
	v_mul_f32_e32 v16, v214, v16
	v_mul_f32_e32 v18, v215, v18
	v_mul_f32_e32 v19, v214, v19
	v_cvt_pk_bf16_f32 v72, v16, v18
	v_mul_f32_e32 v80, v215, v80
	v_cvt_pk_bf16_f32 v80, v19, v80
	s_waitcnt lgkmcnt(13)
	v_lshlrev_b32_e32 v19, 16, v232
	s_waitcnt lgkmcnt(12)
	v_lshlrev_b32_e32 v73, 16, v233
	v_and_b32_e32 v16, 0xffff0000, v232
	v_and_b32_e32 v18, 0xffff0000, v233
	v_mul_f32_e32 v73, v217, v73
	v_mul_f32_e32 v16, v216, v16
	v_mul_f32_e32 v18, v217, v18
	v_mul_f32_e32 v19, v216, v19
	v_cvt_pk_bf16_f32 v81, v19, v73
	v_cvt_pk_bf16_f32 v73, v16, v18
	s_waitcnt lgkmcnt(11)
	v_lshlrev_b32_e32 v19, 16, v234
	s_waitcnt lgkmcnt(10)
	v_lshlrev_b32_e32 v74, 16, v235
	v_and_b32_e32 v16, 0xffff0000, v234
	v_and_b32_e32 v18, 0xffff0000, v235
	v_mul_f32_e32 v74, v219, v74
	v_mul_f32_e32 v16, v218, v16
	v_mul_f32_e32 v18, v219, v18
	v_mul_f32_e32 v19, v218, v19
	v_cvt_pk_bf16_f32 v82, v19, v74
	v_cvt_pk_bf16_f32 v74, v16, v18
	s_waitcnt lgkmcnt(9)
	v_lshlrev_b32_e32 v19, 16, v236
	s_waitcnt lgkmcnt(8)
	v_lshlrev_b32_e32 v75, 16, v237
	v_and_b32_e32 v16, 0xffff0000, v236
	v_and_b32_e32 v18, 0xffff0000, v237
	v_mul_f32_e32 v75, v221, v75
	v_mul_f32_e32 v16, v220, v16
	v_mul_f32_e32 v18, v221, v18
	v_mul_f32_e32 v19, v220, v19
	v_cvt_pk_bf16_f32 v83, v19, v75
	v_cvt_pk_bf16_f32 v75, v16, v18
	s_waitcnt lgkmcnt(7)
	v_lshlrev_b32_e32 v19, 16, v238
	s_waitcnt lgkmcnt(6)
	v_lshlrev_b32_e32 v88, 16, v239
	v_and_b32_e32 v16, 0xffff0000, v238
	v_and_b32_e32 v18, 0xffff0000, v239
	v_mul_f32_e32 v16, v222, v16
	v_mul_f32_e32 v18, v223, v18
	v_mul_f32_e32 v19, v222, v19
	v_cvt_pk_bf16_f32 v84, v16, v18
	v_mul_f32_e32 v88, v223, v88
	v_cvt_pk_bf16_f32 v88, v19, v88
	s_waitcnt lgkmcnt(5)
	v_lshlrev_b32_e32 v19, 16, v240
	s_waitcnt lgkmcnt(4)
	v_lshlrev_b32_e32 v85, 16, v241
	v_and_b32_e32 v16, 0xffff0000, v240
	v_and_b32_e32 v18, 0xffff0000, v241
	v_mul_f32_e32 v85, v225, v85
	v_mul_f32_e32 v16, v224, v16
	v_mul_f32_e32 v18, v225, v18
	v_mul_f32_e32 v19, v224, v19
	v_cvt_pk_bf16_f32 v89, v19, v85
	v_cvt_pk_bf16_f32 v85, v16, v18
	s_waitcnt lgkmcnt(3)
	v_lshlrev_b32_e32 v19, 16, v242
	s_waitcnt lgkmcnt(2)
	v_lshlrev_b32_e32 v86, 16, v243
	v_and_b32_e32 v16, 0xffff0000, v242
	v_and_b32_e32 v18, 0xffff0000, v243
	v_mul_f32_e32 v86, v227, v86
	v_mul_f32_e32 v16, v226, v16
	v_mul_f32_e32 v18, v227, v18
	v_mul_f32_e32 v19, v226, v19
	v_cvt_pk_bf16_f32 v90, v19, v86
	v_cvt_pk_bf16_f32 v86, v16, v18
	s_waitcnt lgkmcnt(1)
	v_lshlrev_b32_e32 v19, 16, v244
	s_waitcnt lgkmcnt(0)
	v_lshlrev_b32_e32 v76, 16, v245
	v_and_b32_e32 v16, 0xffff0000, v244
	v_and_b32_e32 v18, 0xffff0000, v245
	v_mul_f32_e32 v19, v228, v19
	v_mul_f32_e32 v16, v228, v16
	v_mul_f32_e32 v18, v229, v18
	v_mul_f32_e32 v76, v229, v76
	v_cvt_pk_bf16_f32 v91, v19, v76
	v_cvt_pk_bf16_f32 v87, v16, v18
	ds_write_b128 v124, v[80:83]
	ds_write_b128 v124, v[88:91] offset:16
	ds_write_b128 v124, v[72:75] offset:144
	ds_write_b128 v124, v[84:87] offset:160
	s_waitcnt lgkmcnt(0)
	ds_read_b128 v[88:91], v128
	ds_read_b32 v92, v125
	ds_read_b128 v[214:217], v126
	ds_read_b128 v[218:221], v127 offset:33792
	ds_read_b128 v[222:225], v127 offset:42240
	ds_read_b128 v[226:229], v165
	ds_read_b128 v[230:233], v165 offset:8448
	ds_read_b128 v[166:169], v126 offset:64
	ds_read_b128 v[170:173], v127 offset:33856
	ds_read_b128 v[174:177], v127 offset:42304
	ds_read_b128 v[178:181], v165 offset:64
	ds_read_b128 v[182:185], v165 offset:8512
	s_waitcnt lgkmcnt(5)
	v_mfma_f32_16x16x32_bf16 v[76:79], v[218:221], v[214:217], 0
	v_mfma_f32_16x16x32_bf16 v[72:75], v[222:225], v[214:217], 0
	v_mfma_f32_16x16x32_bf16 v[80:83], v[226:229], v[214:217], 0
	v_mfma_f32_16x16x32_bf16 v[84:87], v[230:233], v[214:217], 0
	ds_read_b128 v[214:217], v126 offset:128
	ds_read_b128 v[218:221], v127 offset:33920
	ds_read_b128 v[222:225], v127 offset:42368
	ds_read_b128 v[226:229], v165 offset:128
	ds_read_b128 v[230:233], v165 offset:8576
	s_waitcnt lgkmcnt(5)
	v_mfma_f32_16x16x32_bf16 v[76:79], v[170:173], v[166:169], v[76:79]
	v_mfma_f32_16x16x32_bf16 v[72:75], v[174:177], v[166:169], v[72:75]
	v_mfma_f32_16x16x32_bf16 v[80:83], v[178:181], v[166:169], v[80:83]
	v_mfma_f32_16x16x32_bf16 v[84:87], v[182:185], v[166:169], v[84:87]
	ds_read_b128 v[166:169], v126 offset:192
	ds_read_b128 v[170:173], v127 offset:33984
	ds_read_b128 v[174:177], v127 offset:42432
	ds_read_b128 v[178:181], v165 offset:192
	ds_read_b128 v[182:185], v165 offset:8640
	s_waitcnt lgkmcnt(5)
	v_mfma_f32_16x16x32_bf16 v[76:79], v[218:221], v[214:217], v[76:79]
	v_mfma_f32_16x16x32_bf16 v[72:75], v[222:225], v[214:217], v[72:75]
	v_mfma_f32_16x16x32_bf16 v[80:83], v[226:229], v[214:217], v[80:83]
	v_mfma_f32_16x16x32_bf16 v[84:87], v[230:233], v[214:217], v[84:87]
	ds_read_b128 v[214:217], v126 offset:256
	ds_read_b128 v[218:221], v127 offset:34048
	ds_read_b128 v[222:225], v127 offset:42496
	ds_read_b128 v[226:229], v165 offset:256
	ds_read_b128 v[230:233], v165 offset:8704
	s_waitcnt lgkmcnt(5)
; __device__ __forceinline__ unsigned cvt_pk_bf16(float lo, float hi) { unsigned r; asm("v_cvt_pk_bf16_f32 %0, %1, %2" : "=v"(r) : "v"(lo), "v"(hi)); return r; }
; template <int DK, int DV, bool SEPQ> ...
;     ...
;         for (int ks = 0; ks < DK / 32; ++ks) {
;             const bf16x8 qf = *(const bf16x8*)(QA + (16 * m + fr) * LQ + 32 * ks + 8 * fq);
;             if (do0) { const bf16x8 kf = *(const bf16x8*)(KB + (16 * n0 + fr) * LQ + 32 * ks + 8 * fq); acc0 = __builtin_amdgcn_mfma_f32_16x16x32_bf16(kf, qf, acc0, 0, 0, 0); }
;             if (do1) { const bf16x8 kf = *(const bf16x8*)(KB + (16 * n1 + fr) * LQ + 32 * ks + 8 * fq); acc1 = __builtin_amdgcn_mfma_f32_16x16x32_bf16(kf, qf, acc1, 0, 0, 0); }
;             bf16x8 qs = qf; if (SEPQ) qs = *(const bf16x8*)(QS + (16 * m + fr) * LQ + 32 * ks + 8 * fq);
; #pragma unroll
;             for (int vt = 0; vt < NVTW; ++vt) { const bf16x8 sf = *(const bf16x8*)(ST + (16 * (hw * NVTW + vt) + fr) * LQ + 32 * ks + 8 * fq); O[vt] = __builtin_amdgcn_mfma_f32_16x16x32_bf16(sf, qs, O[vt], 0, 0, 0); }
;         }
; #pragma unroll
;         for (int nn = 0; nn < 2; ++nn) {
;             const int n = 2 * hw + nn; const f32x4 acc = nn == 0 ? acc0 : acc1;
;             const f32x4 gj = *(const f32x4*)(GI + 16 * n + 4 * fq); const int i = 16 * m + fr, j0 = 16 * n + 4 * fq; float p[4];
; #pragma unroll
;             for (int e = 0; e < 4; ++e) p[e] = (j0 + e <= i) ? acc[e] * __expf(gi_i - gj[e]) : 0.f;
;             u32x2 w; w.x = cvt_pk_bf16(p[0], p[1]); w.y = cvt_pk_bf16(p[2], p[3]); *(u32x2*)(P + (16 * m + fr) * LJ + j0) = w;
;         }
;         const float ei = __expf(gi_i);
; #pragma unroll
;         for (int vt = 0; vt < NVTW; ++vt) O[vt] = O[vt] * ei;
	v_mfma_f32_16x16x32_bf16 v[76:79], v[170:173], v[166:169], v[76:79]
	v_mfma_f32_16x16x32_bf16 v[72:75], v[174:177], v[166:169], v[72:75]
	v_mfma_f32_16x16x32_bf16 v[80:83], v[178:181], v[166:169], v[80:83]
	v_mfma_f32_16x16x32_bf16 v[84:87], v[182:185], v[166:169], v[84:87]
	ds_read_b128 v[166:169], v126 offset:320
	ds_read_b128 v[170:173], v127 offset:34112
	ds_read_b128 v[174:177], v127 offset:42560
	ds_read_b128 v[178:181], v165 offset:320
	ds_read_b128 v[182:185], v165 offset:8768
	s_waitcnt lgkmcnt(5)
	v_mfma_f32_16x16x32_bf16 v[76:79], v[218:221], v[214:217], v[76:79]
	v_mfma_f32_16x16x32_bf16 v[72:75], v[222:225], v[214:217], v[72:75]
	v_mfma_f32_16x16x32_bf16 v[80:83], v[226:229], v[214:217], v[80:83]
	v_mfma_f32_16x16x32_bf16 v[84:87], v[230:233], v[214:217], v[84:87]
	ds_read_b128 v[214:217], v126 offset:384
	ds_read_b128 v[218:221], v127 offset:34176
	ds_read_b128 v[222:225], v127 offset:42624
	ds_read_b128 v[226:229], v165 offset:384
	ds_read_b128 v[230:233], v165 offset:8832
	s_waitcnt lgkmcnt(5)
	v_mfma_f32_16x16x32_bf16 v[76:79], v[170:173], v[166:169], v[76:79]
	v_mfma_f32_16x16x32_bf16 v[72:75], v[174:177], v[166:169], v[72:75]
	v_mfma_f32_16x16x32_bf16 v[80:83], v[178:181], v[166:169], v[80:83]
	v_mfma_f32_16x16x32_bf16 v[84:87], v[182:185], v[166:169], v[84:87]
	ds_read_b128 v[166:169], v126 offset:448
	ds_read_b128 v[170:173], v127 offset:34240
	ds_read_b128 v[174:177], v127 offset:42688
	ds_read_b128 v[178:181], v165 offset:448
	ds_read_b128 v[182:185], v165 offset:8896
	s_waitcnt lgkmcnt(5)
	v_mfma_f32_16x16x32_bf16 v[76:79], v[218:221], v[214:217], v[76:79]
	v_mfma_f32_16x16x32_bf16 v[72:75], v[222:225], v[214:217], v[72:75]
	v_mfma_f32_16x16x32_bf16 v[80:83], v[226:229], v[214:217], v[80:83]
	v_mfma_f32_16x16x32_bf16 v[84:87], v[230:233], v[214:217], v[84:87]
	s_waitcnt lgkmcnt(0)
	v_mfma_f32_16x16x32_bf16 v[76:79], v[170:173], v[166:169], v[76:79]
	v_mfma_f32_16x16x32_bf16 v[72:75], v[174:177], v[166:169], v[72:75]
	v_mfma_f32_16x16x32_bf16 v[80:83], v[178:181], v[166:169], v[80:83]
	v_mfma_f32_16x16x32_bf16 v[84:87], v[182:185], v[166:169], v[84:87]
	s_nop 7
	v_cmp_gt_i32_e32 vcc, s89, v132
	s_waitcnt lgkmcnt(0)
	v_sub_f32_e32 v16, v92, v88
	v_mul_f32_e32 v16, 0x3fb8aa3b, v16
	v_exp_f32_e32 v16, v16
	v_sub_f32_e32 v18, v92, v89
	v_sub_f32_e32 v19, v92, v90
	v_mul_f32_e32 v18, 0x3fb8aa3b, v18
	v_mul_f32_e32 v16, v76, v16
	v_mul_f32_e32 v19, 0x3fb8aa3b, v19
	v_sub_f32_e32 v76, v92, v91
	ds_read_b128 v[88:91], v128 offset:64
	v_exp_f32_e32 v18, v18
	v_exp_f32_e32 v19, v19
	v_mul_f32_e32 v76, 0x3fb8aa3b, v76
	v_exp_f32_e32 v76, v76
	v_mul_f32_e32 v18, v77, v18
	v_mul_f32_e32 v19, v78, v19
	v_cndmask_b32_e64 v18, 0, v18, s[50:51]
	v_cndmask_b32_e64 v19, v19, 0, s[52:53]
	v_mul_f32_e32 v76, v79, v76
	v_cndmask_b32_e64 v16, v16, 0, s[48:49]
	v_cndmask_b32_e64 v76, v76, 0, s[54:55]
	v_cvt_pk_bf16_f32 v18, v16, v18
	v_cvt_pk_bf16_f32 v19, v19, v76
	ds_write_b64 v129, v[18:19]
	s_waitcnt lgkmcnt(1)
	v_sub_f32_e32 v16, v92, v88
	v_mul_f32_e32 v16, 0x3fb8aa3b, v16
	v_sub_f32_e32 v18, v92, v89
	v_exp_f32_e32 v16, v16
	v_mul_f32_e32 v18, 0x3fb8aa3b, v18
	v_exp_f32_e32 v18, v18
	v_sub_f32_e32 v19, v92, v90
	v_mul_f32_e32 v16, v72, v16
	v_sub_f32_e32 v72, v92, v91
	v_mul_f32_e32 v18, v73, v18
	v_mul_f32_e32 v19, 0x3fb8aa3b, v19
	v_mul_f32_e32 v72, 0x3fb8aa3b, v72
	v_cndmask_b32_e64 v16, v16, 0, s[56:57]
	v_cndmask_b32_e64 v18, 0, v18, s[58:59]
	v_exp_f32_e32 v19, v19
	v_exp_f32_e32 v72, v72
	v_cvt_pk_bf16_f32 v18, v16, v18
	v_mul_f32_e32 v16, 0x3fb8aa3b, v92
	v_exp_f32_e32 v16, v16
	v_mul_f32_e32 v19, v74, v19
	v_mul_f32_e32 v72, v75, v72
	v_cndmask_b32_e64 v19, v19, 0, s[60:61]
	v_cndmask_b32_e64 v72, v72, 0, s[62:63]
	v_cvt_pk_bf16_f32 v19, v19, v72
	ds_write_b64 v129, v[18:19] offset:32
	v_pk_mul_f32 v[72:73], v[16:17], v[80:81] op_sel_hi:[0,1]
	v_pk_mul_f32 v[74:75], v[16:17], v[82:83] op_sel_hi:[0,1]
	v_pk_mul_f32 v[76:77], v[16:17], v[84:85] op_sel_hi:[0,1]
	v_pk_mul_f32 v[78:79], v[16:17], v[86:87] op_sel_hi:[0,1]
	s_waitcnt lgkmcnt(0)
	s_barrier
; __device__ __forceinline__ unsigned cvt_pk_bf16(float lo, float hi) { unsigned r; asm("v_cvt_pk_bf16_f32 %0, %1, %2" : "=v"(r) : "v"(lo), "v"(hi)); return r; }
; template <int DK, int DV, bool SEPQ> ...
;     ...
; #pragma unroll
;     for (int ks = 0; ks < 2; ++ks) { const bf16x8 pf = *(const bf16x8*)(P + (16 * m + fr) * LJ + 32 * ks + 8 * fq);
; #pragma unroll
;         for (int vt = 0; vt < NVTW; ++vt) { const bf16x8 vf = *(const bf16x8*)(VT + (16 * (hw * NVTW + vt) + fr) * LJ + 32 * ks + 8 * fq); O[vt] = __builtin_amdgcn_mfma_f32_16x16x32_bf16(vf, pf, O[vt], 0, 0, 0); } }
; #pragma unroll
;     for (int ct = 0; ct < NCTW; ++ct) { const int ctg = wid * NCTW + ct; const f32x4 dec = *(const f32x4*)(SDEC + 16 * ctg + 4 * fq);
; #pragma unroll
;         for (int vt = 0; vt < NVT; ++vt) S[ct][vt] = S[ct][vt] * dec;
; #pragma unroll
;         for (int ks = 0; ks < 2; ++ks) { const bf16x8 kf = *(const bf16x8*)(KT + (16 * ctg + fr) * LJ + 32 * ks + 8 * fq);
; #pragma unroll
;             for (int vt = 0; vt < NVT; ++vt) { const bf16x8 vf = *(const bf16x8*)(VT2 + (16 * vt + fr) * LJ + 32 * ks + 8 * fq); S[ct][vt] = __builtin_amdgcn_mfma_f32_16x16x32_bf16(kf, vf, S[ct][vt], 0, 0, 0); } } }
; __device__ __forceinline__ void ret_block(ArgsP a_, unsigned char* smem) { const ArgsP a = a_;
;     ...
;         const int m = wid >> 1, hw = wid & 1, i = 16 * m + fr;
;         if (i < len) {
; #pragma unroll
;             for (int vt = 0; vt < 2; ++vt) *(u32x2*)(OB + (size_t)(row0 + i) * 2048 + h * 512 + vs * 64 + 16 * (hw * 2 + vt) + 4 * fq) = (u32x2){cvt_pk_bf16(O[vt][0], O[vt][1]), cvt_pk_bf16(O[vt][2], O[vt][3])}; }
	ds_read_b128 v[214:217], v130
	ds_read_b128 v[218:221], v144
	ds_read_b128 v[222:225], v144 offset:2304
	ds_read_b128 v[226:229], v130 offset:64
	ds_read_b128 v[230:233], v144 offset:64
	ds_read_b128 v[234:237], v144 offset:2368
	ds_read_b128 v[238:241], v131
	ds_read_b128 v[242:245], v145
	ds_read_b128 v[246:249], v147
	ds_read_b128 v[166:169], v147 offset:2304
	ds_read_b128 v[170:173], v147 offset:4608
	ds_read_b128 v[174:177], v147 offset:6912
	ds_read_b128 v[178:181], v145 offset:64
	ds_read_b128 v[182:185], v147 offset:64
	ds_read_b128 v[80:83], v147 offset:2368
	s_waitcnt lgkmcnt(13)
	v_mfma_f32_16x16x32_bf16 v[72:75], v[218:221], v[214:217], v[72:75]
	ds_read_b128 v[84:87], v147 offset:4672
	ds_read_b128 v[88:91], v147 offset:6976
	s_waitcnt lgkmcnt(14)
	v_mfma_f32_16x16x32_bf16 v[76:79], v[222:225], v[214:217], v[76:79]
	ds_read_b128 v[218:221], v131 offset:64
	s_waitcnt lgkmcnt(13)
	v_mfma_f32_16x16x32_bf16 v[72:75], v[230:233], v[226:229], v[72:75]
	ds_read_b128 v[214:217], v164
	ds_read_b128 v[222:225], v164 offset:64
	s_waitcnt lgkmcnt(14)
	v_mfma_f32_16x16x32_bf16 v[76:79], v[234:237], v[226:229], v[76:79]
	s_waitcnt lgkmcnt(13)
	v_pk_mul_f32 v[42:43], v[42:43], v[240:241]
	v_pk_mul_f32 v[40:41], v[40:41], v[238:239]
	v_pk_mul_f32 v[46:47], v[46:47], v[240:241]
	v_pk_mul_f32 v[44:45], v[44:45], v[238:239]
	v_pk_mul_f32 v[50:51], v[50:51], v[240:241]
	v_pk_mul_f32 v[48:49], v[48:49], v[238:239]
	v_pk_mul_f32 v[54:55], v[54:55], v[240:241]
	v_pk_mul_f32 v[52:53], v[52:53], v[238:239]
	s_waitcnt lgkmcnt(11)
	v_mfma_f32_16x16x32_bf16 v[40:43], v[242:245], v[246:249], v[40:43]
	s_waitcnt lgkmcnt(10)
	v_mfma_f32_16x16x32_bf16 v[44:47], v[242:245], v[166:169], v[44:47]
	s_waitcnt lgkmcnt(9)
	v_mfma_f32_16x16x32_bf16 v[48:51], v[242:245], v[170:173], v[48:51]
	s_waitcnt lgkmcnt(8)
	v_mfma_f32_16x16x32_bf16 v[52:55], v[242:245], v[174:177], v[52:55]
	s_waitcnt lgkmcnt(6)
	v_mfma_f32_16x16x32_bf16 v[40:43], v[178:181], v[182:185], v[40:43]
	s_waitcnt lgkmcnt(5)
	v_mfma_f32_16x16x32_bf16 v[44:47], v[178:181], v[80:83], v[44:47]
	s_waitcnt lgkmcnt(4)
	v_mfma_f32_16x16x32_bf16 v[48:51], v[178:181], v[84:87], v[48:51]
	s_waitcnt lgkmcnt(3)
	v_mfma_f32_16x16x32_bf16 v[52:55], v[178:181], v[88:91], v[52:55]
	s_waitcnt lgkmcnt(2)
	v_pk_mul_f32 v[58:59], v[58:59], v[220:221]
	v_pk_mul_f32 v[56:57], v[56:57], v[218:219]
	v_pk_mul_f32 v[62:63], v[62:63], v[220:221]
	v_pk_mul_f32 v[60:61], v[60:61], v[218:219]
	v_pk_mul_f32 v[66:67], v[66:67], v[220:221]
	v_pk_mul_f32 v[64:65], v[64:65], v[218:219]
	v_pk_mul_f32 v[70:71], v[70:71], v[220:221]
	v_pk_mul_f32 v[68:69], v[68:69], v[218:219]
	s_waitcnt lgkmcnt(1)
	v_mfma_f32_16x16x32_bf16 v[56:59], v[214:217], v[246:249], v[56:59]
	v_mfma_f32_16x16x32_bf16 v[60:63], v[214:217], v[166:169], v[60:63]
	v_mfma_f32_16x16x32_bf16 v[64:67], v[214:217], v[170:173], v[64:67]
	v_mfma_f32_16x16x32_bf16 v[68:71], v[214:217], v[174:177], v[68:71]
	s_waitcnt lgkmcnt(0)
	v_mfma_f32_16x16x32_bf16 v[56:59], v[222:225], v[182:185], v[56:59]
	v_mfma_f32_16x16x32_bf16 v[60:63], v[222:225], v[80:83], v[60:63]
	v_mfma_f32_16x16x32_bf16 v[64:67], v[222:225], v[84:87], v[64:67]
	v_mfma_f32_16x16x32_bf16 v[68:71], v[222:225], v[88:91], v[68:71]
	s_and_saveexec_b64 s[64:65], vcc
	s_cbranch_execz .LBB0_303
	v_add_u32_e32 v18, s88, v132
	v_ashrrev_i32_e32 v19, 31, v18
	v_lshlrev_b64 v[18:19], 12, v[18:19]
	v_lshl_add_u64 v[18:19], s[26:27], 0, v[18:19]
	s_lshl_b32 s70, s91, 10
	s_mov_b32 s71, s12
	v_lshl_add_u64 v[18:19], v[18:19], 0, s[70:71]
	s_lshl_b32 s70, s90, 7
	v_lshl_add_u64 v[18:19], v[18:19], 0, s[70:71]
	v_mov_b32_e32 v113, v17
	v_lshl_add_u64 v[18:19], v[18:19], 0, v[112:113]
	v_mov_b32_e32 v115, v17
	v_cvt_pk_bf16_f32 v72, v72, v73
	v_cvt_pk_bf16_f32 v73, v74, v75
	v_lshl_add_u64 v[18:19], v[18:19], 0, v[114:115]
	global_store_dwordx2 v[18:19], v[72:73], off
	v_cvt_pk_bf16_f32 v72, v76, v77
	v_cvt_pk_bf16_f32 v73, v78, v79
	global_store_dwordx2 v[18:19], v[72:73], off offset:32
